# RMS+forget loop: next-row software prefetch (saddr loads into spare registers, copied in at the original load points)
# speedup vs baseline: 1.0174x; 1.0080x over previous
.LBB0_638:
	s_or_b64 exec, exec, s[24:25]
	v_ashrrev_i32_e32 v0, 6, v2
	v_readlane_b32 s4, v254, 18
	s_waitcnt vmcnt(0) lgkmcnt(0)
	s_barrier
	v_add_u32_e32 v142, s4, v0
	s_mov_b32 s4, 0x8100
	v_cmp_gt_i32_e32 vcc, s4, v142
	s_and_saveexec_b64 s[24:25], vcc
	s_cbranch_execz .LBB0_649
	v_and_b32_e32 v0, 64, v218
	v_add_u32_e32 v0, 64, v0
	v_xor_b32_e32 v3, 1, v218
	v_cmp_lt_i32_e32 vcc, v3, v0
	s_add_u32 s48, s44, 0x8000000
	s_addc_u32 s49, s45, 0
	v_cndmask_b32_e32 v3, v218, v3, vcc
	v_lshlrev_b32_e32 v160, 2, v3
	v_xor_b32_e32 v3, 2, v218
	v_cmp_lt_i32_e32 vcc, v3, v0
	s_lshl_b32 s28, s64, 3
	s_lshl_b64 s[4:5], s[28:29], 2
	v_cndmask_b32_e32 v3, v218, v3, vcc
	v_lshlrev_b32_e32 v161, 2, v3
	v_xor_b32_e32 v3, 4, v218
	v_cmp_lt_i32_e32 vcc, v3, v0
	s_add_u32 s8, s38, s4
	v_and_b32_e32 v130, 63, v2
	v_cndmask_b32_e32 v3, v218, v3, vcc
	v_lshlrev_b32_e32 v162, 2, v3
	v_xor_b32_e32 v3, 8, v218
	v_cmp_lt_i32_e32 vcc, v3, v0
	s_addc_u32 s9, s39, s5
	v_lshl_add_u32 v126, v130, 4, 0
	v_cndmask_b32_e32 v3, v218, v3, vcc
	v_lshlrev_b32_e32 v163, 2, v3
	v_xor_b32_e32 v3, 16, v218
	v_cmp_lt_i32_e32 vcc, v3, v0
	s_lshl_b64 s[4:5], s[64:65], 20
	s_add_u32 s4, s44, s4
	v_cndmask_b32_e32 v3, v218, v3, vcc
	v_lshlrev_b32_e32 v164, 2, v3
	v_xor_b32_e32 v3, 32, v218
	v_cmp_lt_i32_e32 vcc, v3, v0
	s_addc_u32 s5, s45, s5
	s_add_u32 s4, s4, 0x1831c000
	v_cndmask_b32_e32 v0, v218, v3, vcc
	v_lshlrev_b32_e32 v165, 2, v0
	v_and_b32_e32 v0, 1, v2
	v_and_b32_e32 v3, 2, v2
	v_cmp_eq_u32_e32 vcc, 0, v0
	v_lshlrev_b32_e32 v0, 2, v130
	v_cmp_eq_u32_e64 s[38:39], 0, v3
	v_and_b32_e32 v3, 4, v2
	v_xor_b32_e32 v166, 4, v0
	v_xor_b32_e32 v167, 8, v0
	v_cmp_eq_u32_e64 s[40:41], 0, v3
	v_xor_b32_e32 v168, 16, v0
	v_xor_b32_e32 v169, 32, v0
	v_xor_b32_e32 v170, 64, v0
	v_xor_b32_e32 v171, 0x80, v0
	v_bfrev_b32_e32 v0, v2
	ds_read_b128 v[2:5], v126
	ds_read_b128 v[6:9], v126 offset:1024
	ds_read_b128 v[10:13], v126 offset:2048
	ds_read_b128 v[14:17], v126 offset:3072
	ds_read_b128 v[18:21], v126 offset:4096
	ds_read_b128 v[22:25], v126 offset:5120
	ds_read_b128 v[26:29], v126 offset:6144
	ds_read_b128 v[30:33], v126 offset:7168
	ds_read_b128 v[34:37], v126 offset:8192
	ds_read_b128 v[38:41], v126 offset:9216
	ds_read_b128 v[42:45], v126 offset:10240
	ds_read_b128 v[46:49], v126 offset:11264
	ds_read_b128 v[50:53], v126 offset:12288
	ds_read_b128 v[54:57], v126 offset:13312
	ds_read_b128 v[58:61], v126 offset:14336
	ds_read_b128 v[62:65], v126 offset:15360
	ds_read_b128 v[66:69], v126 offset:16384
	ds_read_b128 v[70:73], v126 offset:17408
	ds_read_b128 v[74:77], v126 offset:18432
	ds_read_b128 v[78:81], v126 offset:19456
	ds_read_b128 v[82:85], v126 offset:20480
	ds_read_b128 v[86:89], v126 offset:21504
	ds_read_b128 v[90:93], v126 offset:22528
	ds_read_b128 v[94:97], v126 offset:23552
	ds_read_b128 v[98:101], v126 offset:24576
	ds_read_b128 v[102:105], v126 offset:25600
	ds_read_b128 v[106:109], v126 offset:26624
	ds_read_b128 v[110:113], v126 offset:27648
	ds_read_b128 v[114:117], v126 offset:28672
	ds_read_b128 v[118:121], v126 offset:29696
	ds_read_b128 v[122:125], v126 offset:30720
	ds_read_b128 v[126:129], v126 offset:31744
	s_addc_u32 s5, s5, 0
	s_lshl_b64 s[10:11], s[64:65], 13
	s_add_u32 s10, s44, s10
	v_lshrrev_b32_e32 v132, 29, v0
	s_addc_u32 s11, s45, s11
	v_lshlrev_b32_e32 v0, 2, v132
	v_ashrrev_i32_e32 v143, 31, v142
	s_add_u32 s28, s10, 0x1871c000
	v_lshl_add_u64 v[144:145], s[8:9], 0, v[0:1]
	v_lshlrev_b32_e32 v0, 3, v130
	v_lshlrev_b64 v[134:135], 12, v[142:143]
	s_addc_u32 s52, s11, 0
	v_cmp_gt_u32_e64 s[42:43], 8, v130
	v_lshl_add_u64 v[146:147], s[78:79], 0, v[0:1]
	v_lshl_add_u64 v[148:149], s[44:45], 0, v[134:135]
	s_mov_b64 s[50:51], 0
	v_lshlrev_b32_e32 v0, 4, v130
	v_lshlrev_b32_e32 v150, 2, v132
	s_mov_b64 s[100:101], s[44:45]
	v_lshl_or_b32 v240, v142, 12, v0
	global_load_dwordx4 v[224:227], v240, s[100:101]
	global_load_dwordx4 v[228:231], v240, s[100:101] offset:1024
	global_load_dwordx4 v[232:235], v240, s[100:101] offset:2048
	global_load_dwordx4 v[236:239], v240, s[100:101] offset:3072
	s_waitcnt vmcnt(0)
	s_branch .LBB0_642

.LBB0_642:
	s_waitcnt vmcnt(1)
	s_mov_b32 s8, 0x8000
	v_cmp_gt_i32_e64 s[44:45], s8, v142
	v_cmp_lt_i32_e64 s[46:47], s91, v142
	v_add_u32_e32 v152, 0xffff8000, v142
	v_mov_b64_e32 v[154:155], v[142:143]
	s_waitcnt lgkmcnt(0)
	v_mov_b64_e32 v[130:131], v[148:149]
	s_and_saveexec_b64 s[54:55], s[46:47]
	v_mov_b32_e32 v153, v1
	v_lshlrev_b64 v[130:131], 12, v[152:153]
	v_lshl_add_u64 v[130:131], s[48:49], 0, v[130:131]
	v_mov_b32_e32 v154, v142
	v_mov_b32_e32 v155, v1
	s_or_b64 exec, exec, s[54:55]
	v_lshl_add_u64 v[130:131], v[130:131], 0, v[0:1]
	v_mov_b64_e32 v[172:173], v[224:225]
	v_mov_b64_e32 v[174:175], v[226:227]
	v_mov_b64_e32 v[138:139], v[228:229]
	v_mov_b64_e32 v[140:141], v[230:231]
	s_mov_b32 s8, 0x800000
	v_pk_mul_f32 v[132:133], v[174:175], v[174:175]
	v_pk_mul_f32 v[134:135], v[172:173], v[172:173]
	s_nop 0
	v_pk_mov_b32 v[136:137], v[134:135], v[132:133] op_sel:[1,0]
	v_mov_b32_e32 v135, v133
	v_pk_add_f32 v[156:157], v[136:137], v[134:135]
	v_pk_mul_f32 v[132:133], v[140:141], v[140:141]
	v_pk_mul_f32 v[134:135], v[138:139], v[138:139]
	v_pk_add_f32 v[156:157], v[156:157], v[156:157] op_sel:[0,1] op_sel_hi:[1,0]
	v_pk_mov_b32 v[136:137], v[134:135], v[132:133] op_sel:[1,0]
	v_mov_b32_e32 v135, v133
	v_pk_add_f32 v[158:159], v[136:137], v[134:135]
	v_mov_b64_e32 v[134:135], v[232:233]
	v_mov_b64_e32 v[136:137], v[234:235]
	s_nop 0
	v_mov_b64_e32 v[130:131], v[236:237]
	v_mov_b64_e32 v[132:133], v[238:239]
	v_readlane_b32 s10, v254, 55
	s_mov_b32 s11, 0x80ff
	v_add_u32_e32 v240, s10, v142
	v_min_i32_e32 v240, s11, v240
	v_lshl_or_b32 v240, v240, 12, v0
	global_load_dwordx4 v[224:227], v240, s[100:101]
	global_load_dwordx4 v[228:231], v240, s[100:101] offset:1024
	global_load_dwordx4 v[232:235], v240, s[100:101] offset:2048
	global_load_dwordx4 v[236:239], v240, s[100:101] offset:3072
	v_pk_add_f32 v[158:159], v[158:159], v[158:159] op_sel:[0,1] op_sel_hi:[1,0]
	v_mul_f32_e32 v151, v130, v130
	v_mul_f32_e32 v153, v131, v131
	v_mov_b32_e32 v157, v151
	v_mov_b32_e32 v159, v153
	v_pk_add_f32 v[156:157], v[156:157], v[158:159]
	v_mul_f32_e32 v158, v135, v135
	v_mul_f32_e32 v176, v132, v132
	v_pk_fma_f32 v[158:159], v[134:135], v[134:135], v[158:159] op_sel_hi:[1,1,0]
	v_mul_f32_e32 v178, v133, v133
	v_mov_b32_e32 v159, v176
	v_mul_f32_e32 v176, v137, v137
	v_pk_fma_f32 v[176:177], v[136:137], v[136:137], v[176:177] op_sel_hi:[1,1,0]
	s_nop 0
	v_mov_b32_e32 v177, v178
	v_pk_add_f32 v[158:159], v[158:159], v[176:177]
	v_lshlrev_b64 v[178:179], 11, v[154:155]
	v_pk_add_f32 v[156:157], v[156:157], v[158:159]
	s_nop 0
	v_add_f32_e32 v151, v156, v157
	ds_bpermute_b32 v153, v160, v151
	s_waitcnt lgkmcnt(0)
	v_add_f32_e32 v151, v151, v153
	ds_bpermute_b32 v153, v161, v151
	s_waitcnt lgkmcnt(0)
	v_add_f32_e32 v151, v151, v153
	ds_bpermute_b32 v153, v162, v151
	s_waitcnt lgkmcnt(0)
	v_add_f32_e32 v151, v151, v153
	ds_bpermute_b32 v153, v163, v151
	s_waitcnt lgkmcnt(0)
	v_add_f32_e32 v151, v151, v153
	ds_bpermute_b32 v153, v164, v151
	s_waitcnt lgkmcnt(0)
	v_add_f32_e32 v151, v151, v153
	ds_bpermute_b32 v153, v165, v151
	s_waitcnt lgkmcnt(0)
	v_add_f32_e32 v151, v151, v153
	v_fmamk_f32 v151, v151, 0x3a800000, v206
	v_cmp_gt_f32_e64 s[46:47], s8, v151
	v_mul_f32_e32 v153, 0x4b800000, v151
	s_nop 0
	v_cndmask_b32_e64 v151, v151, v153, s[46:47]
	v_rsq_f32_e32 v151, v151
	s_nop 0
	v_mul_f32_e32 v153, 0x45800000, v151
	v_cndmask_b32_e64 v176, v151, v153, s[46:47]
	v_pk_mul_f32 v[156:157], v[174:175], v[176:177] op_sel_hi:[1,0]
	v_pk_mul_f32 v[158:159], v[172:173], v[176:177] op_sel_hi:[1,0]
	v_and_b32_sdwa v172, v157, v205 dst_sel:DWORD dst_unused:UNUSED_PAD src0_sel:WORD_1 src1_sel:DWORD
	v_and_b32_sdwa v173, v159, v205 dst_sel:DWORD dst_unused:UNUSED_PAD src0_sel:WORD_1 src1_sel:DWORD
	v_and_b32_sdwa v151, v156, v205 dst_sel:DWORD dst_unused:UNUSED_PAD src0_sel:WORD_1 src1_sel:DWORD
	v_and_b32_sdwa v153, v158, v205 dst_sel:DWORD dst_unused:UNUSED_PAD src0_sel:WORD_1 src1_sel:DWORD
	v_add3_u32 v172, v157, v172, s91
	v_add3_u32 v173, v159, v173, s91
	v_add3_u32 v153, v158, v153, s91
	v_add3_u32 v151, v156, v151, s91
	v_and_b32_e32 v172, 0xffff0000, v172
	v_and_b32_e32 v174, 0xffff0000, v173
	v_or_b32_sdwa v173, v172, v151 dst_sel:DWORD dst_unused:UNUSED_PAD src0_sel:DWORD src1_sel:WORD_1
	v_or_b32_sdwa v172, v174, v153 dst_sel:DWORD dst_unused:UNUSED_PAD src0_sel:DWORD src1_sel:WORD_1
	v_lshl_add_u64 v[174:175], v[146:147], 0, v[178:179]
	v_pk_mul_f32 v[140:141], v[140:141], v[176:177] op_sel_hi:[1,0]
	v_pk_mul_f32 v[138:139], v[138:139], v[176:177] op_sel_hi:[1,0]
	global_store_dwordx2 v[174:175], v[172:173], off
	v_and_b32_sdwa v172, v141, v205 dst_sel:DWORD dst_unused:UNUSED_PAD src0_sel:WORD_1 src1_sel:DWORD
	v_and_b32_sdwa v173, v139, v205 dst_sel:DWORD dst_unused:UNUSED_PAD src0_sel:WORD_1 src1_sel:DWORD
	v_and_b32_sdwa v151, v140, v205 dst_sel:DWORD dst_unused:UNUSED_PAD src0_sel:WORD_1 src1_sel:DWORD
	v_and_b32_sdwa v153, v138, v205 dst_sel:DWORD dst_unused:UNUSED_PAD src0_sel:WORD_1 src1_sel:DWORD
	v_add3_u32 v172, v141, v172, s91
	v_add3_u32 v173, v139, v173, s91
	v_add3_u32 v153, v138, v153, s91
	v_add3_u32 v151, v140, v151, s91
	v_and_b32_e32 v172, 0xffff0000, v172
	v_and_b32_e32 v177, 0xffff0000, v173
	v_or_b32_sdwa v173, v172, v151 dst_sel:DWORD dst_unused:UNUSED_PAD src0_sel:DWORD src1_sel:WORD_1
	v_or_b32_sdwa v172, v177, v153 dst_sel:DWORD dst_unused:UNUSED_PAD src0_sel:DWORD src1_sel:WORD_1
	v_pk_mul_f32 v[136:137], v[136:137], v[176:177] op_sel_hi:[1,0]
	v_pk_mul_f32 v[134:135], v[134:135], v[176:177] op_sel_hi:[1,0]
	global_store_dwordx2 v[174:175], v[172:173], off offset:512
	v_and_b32_sdwa v172, v137, v205 dst_sel:DWORD dst_unused:UNUSED_PAD src0_sel:WORD_1 src1_sel:DWORD
	v_and_b32_sdwa v173, v135, v205 dst_sel:DWORD dst_unused:UNUSED_PAD src0_sel:WORD_1 src1_sel:DWORD
	v_and_b32_sdwa v151, v136, v205 dst_sel:DWORD dst_unused:UNUSED_PAD src0_sel:WORD_1 src1_sel:DWORD
	v_and_b32_sdwa v153, v134, v205 dst_sel:DWORD dst_unused:UNUSED_PAD src0_sel:WORD_1 src1_sel:DWORD
	v_add3_u32 v172, v137, v172, s91
	v_add3_u32 v173, v135, v173, s91
	v_add3_u32 v153, v134, v153, s91
	v_add3_u32 v151, v136, v151, s91
	v_and_b32_e32 v172, 0xffff0000, v172
	v_and_b32_e32 v177, 0xffff0000, v173
	v_or_b32_sdwa v173, v172, v151 dst_sel:DWORD dst_unused:UNUSED_PAD src0_sel:DWORD src1_sel:WORD_1
	v_or_b32_sdwa v172, v177, v153 dst_sel:DWORD dst_unused:UNUSED_PAD src0_sel:DWORD src1_sel:WORD_1
	v_pk_mul_f32 v[132:133], v[132:133], v[176:177] op_sel_hi:[1,0]
	v_pk_mul_f32 v[130:131], v[130:131], v[176:177] op_sel_hi:[1,0]
	global_store_dwordx2 v[174:175], v[172:173], off offset:1024
	v_and_b32_sdwa v172, v133, v205 dst_sel:DWORD dst_unused:UNUSED_PAD src0_sel:WORD_1 src1_sel:DWORD
	v_and_b32_sdwa v173, v131, v205 dst_sel:DWORD dst_unused:UNUSED_PAD src0_sel:WORD_1 src1_sel:DWORD
	v_and_b32_sdwa v151, v132, v205 dst_sel:DWORD dst_unused:UNUSED_PAD src0_sel:WORD_1 src1_sel:DWORD
	v_and_b32_sdwa v153, v130, v205 dst_sel:DWORD dst_unused:UNUSED_PAD src0_sel:WORD_1 src1_sel:DWORD
	v_add3_u32 v172, v133, v172, s91
	v_add3_u32 v173, v131, v173, s91
	v_add3_u32 v153, v130, v153, s91
	v_add3_u32 v151, v132, v151, s91
	v_and_b32_e32 v172, 0xffff0000, v172
	v_and_b32_e32 v176, 0xffff0000, v173
	v_or_b32_sdwa v173, v172, v151 dst_sel:DWORD dst_unused:UNUSED_PAD src0_sel:DWORD src1_sel:WORD_1
	v_or_b32_sdwa v172, v176, v153 dst_sel:DWORD dst_unused:UNUSED_PAD src0_sel:DWORD src1_sel:WORD_1
	global_store_dwordx2 v[174:175], v[172:173], off offset:1536
	v_pk_mul_f32 v[180:181], v[2:3], v[158:159]
	v_pk_mul_f32 v[182:183], v[18:19], v[158:159]
	v_pk_mul_f32 v[184:185], v[34:35], v[158:159]
	v_pk_mul_f32 v[186:187], v[50:51], v[158:159]
	v_pk_fma_f32 v[180:181], v[4:5], v[156:157], v[180:181]
	v_pk_fma_f32 v[182:183], v[20:21], v[156:157], v[182:183]
	v_pk_fma_f32 v[184:185], v[36:37], v[156:157], v[184:185]
	v_pk_fma_f32 v[186:187], v[52:53], v[156:157], v[186:187]
	v_pk_fma_f32 v[180:181], v[6:7], v[138:139], v[180:181]
	v_pk_fma_f32 v[182:183], v[22:23], v[138:139], v[182:183]
	v_pk_fma_f32 v[184:185], v[38:39], v[138:139], v[184:185]
	v_pk_fma_f32 v[186:187], v[54:55], v[138:139], v[186:187]
	v_pk_fma_f32 v[180:181], v[8:9], v[140:141], v[180:181]
	v_pk_fma_f32 v[182:183], v[24:25], v[140:141], v[182:183]
	v_pk_fma_f32 v[184:185], v[40:41], v[140:141], v[184:185]
	v_pk_fma_f32 v[186:187], v[56:57], v[140:141], v[186:187]
	v_pk_fma_f32 v[180:181], v[10:11], v[134:135], v[180:181]
	v_pk_fma_f32 v[182:183], v[26:27], v[134:135], v[182:183]
	v_pk_fma_f32 v[184:185], v[42:43], v[134:135], v[184:185]
	v_pk_fma_f32 v[186:187], v[58:59], v[134:135], v[186:187]
	v_pk_fma_f32 v[180:181], v[12:13], v[136:137], v[180:181]
	v_pk_fma_f32 v[182:183], v[28:29], v[136:137], v[182:183]
	v_pk_fma_f32 v[184:185], v[44:45], v[136:137], v[184:185]
	v_pk_fma_f32 v[186:187], v[60:61], v[136:137], v[186:187]
	v_pk_fma_f32 v[180:181], v[14:15], v[130:131], v[180:181]
	v_pk_fma_f32 v[182:183], v[30:31], v[130:131], v[182:183]
	v_pk_fma_f32 v[184:185], v[46:47], v[130:131], v[184:185]
	v_pk_fma_f32 v[186:187], v[62:63], v[130:131], v[186:187]
	v_pk_fma_f32 v[180:181], v[16:17], v[132:133], v[180:181]
	v_pk_fma_f32 v[182:183], v[32:33], v[132:133], v[182:183]
	v_pk_fma_f32 v[184:185], v[48:49], v[132:133], v[184:185]
	v_pk_fma_f32 v[186:187], v[64:65], v[132:133], v[186:187]
	v_add_f32_e32 v151, v180, v181
	v_add_f32_e32 v153, v182, v183
	v_add_f32_e32 v172, v184, v185
	v_add_f32_e32 v173, v186, v187
	v_pk_mul_f32 v[180:181], v[66:67], v[158:159]
	v_pk_mul_f32 v[182:183], v[82:83], v[158:159]
	v_pk_mul_f32 v[184:185], v[98:99], v[158:159]
	v_pk_mul_f32 v[186:187], v[114:115], v[158:159]
	v_pk_fma_f32 v[180:181], v[68:69], v[156:157], v[180:181]
	v_pk_fma_f32 v[182:183], v[84:85], v[156:157], v[182:183]
	v_pk_fma_f32 v[184:185], v[100:101], v[156:157], v[184:185]
	v_pk_fma_f32 v[186:187], v[116:117], v[156:157], v[186:187]
	v_pk_fma_f32 v[180:181], v[70:71], v[138:139], v[180:181]
	v_pk_fma_f32 v[182:183], v[86:87], v[138:139], v[182:183]
	v_pk_fma_f32 v[184:185], v[102:103], v[138:139], v[184:185]
	v_pk_fma_f32 v[186:187], v[118:119], v[138:139], v[186:187]
	v_pk_fma_f32 v[180:181], v[72:73], v[140:141], v[180:181]
	v_pk_fma_f32 v[182:183], v[88:89], v[140:141], v[182:183]
	v_pk_fma_f32 v[184:185], v[104:105], v[140:141], v[184:185]
	v_pk_fma_f32 v[186:187], v[120:121], v[140:141], v[186:187]
	v_pk_fma_f32 v[180:181], v[74:75], v[134:135], v[180:181]
	v_pk_fma_f32 v[182:183], v[90:91], v[134:135], v[182:183]
	v_pk_fma_f32 v[184:185], v[106:107], v[134:135], v[184:185]
	v_pk_fma_f32 v[186:187], v[122:123], v[134:135], v[186:187]
	v_pk_fma_f32 v[180:181], v[76:77], v[136:137], v[180:181]
	v_pk_fma_f32 v[182:183], v[92:93], v[136:137], v[182:183]
	v_pk_fma_f32 v[184:185], v[108:109], v[136:137], v[184:185]
	v_pk_fma_f32 v[186:187], v[124:125], v[136:137], v[186:187]
	v_pk_fma_f32 v[180:181], v[78:79], v[130:131], v[180:181]
	v_pk_fma_f32 v[182:183], v[94:95], v[130:131], v[182:183]
	v_pk_fma_f32 v[184:185], v[110:111], v[130:131], v[184:185]
	v_pk_fma_f32 v[186:187], v[126:127], v[130:131], v[186:187]
	v_pk_fma_f32 v[180:181], v[80:81], v[132:133], v[180:181]
	v_pk_fma_f32 v[182:183], v[96:97], v[132:133], v[182:183]
	v_pk_fma_f32 v[184:185], v[112:113], v[132:133], v[184:185]
	v_pk_fma_f32 v[186:187], v[128:129], v[132:133], v[186:187]
	v_add_f32_e32 v174, v180, v181
	v_add_f32_e32 v175, v182, v183
	v_add_f32_e32 v176, v184, v185
	v_add_f32_e32 v130, v186, v187
	v_cndmask_b32_e32 v131, v151, v174, vcc
	v_cndmask_b32_e32 v132, v153, v175, vcc
	v_cndmask_b32_e32 v133, v172, v176, vcc
	v_cndmask_b32_e32 v134, v173, v130, vcc
	ds_bpermute_b32 v131, v166, v131
	ds_bpermute_b32 v132, v166, v132
	ds_bpermute_b32 v133, v166, v133
	ds_bpermute_b32 v134, v166, v134
	v_cndmask_b32_e32 v180, v174, v151, vcc
	v_cndmask_b32_e32 v181, v175, v153, vcc
	v_cndmask_b32_e32 v182, v176, v172, vcc
	v_cndmask_b32_e32 v183, v130, v173, vcc
	s_waitcnt lgkmcnt(0)
	v_add_f32_e32 v131, v180, v131
	v_add_f32_e32 v132, v181, v132
	v_add_f32_e32 v133, v182, v133
	v_add_f32_e32 v130, v183, v134
	v_cndmask_b32_e64 v134, v131, v133, s[38:39]
	v_cndmask_b32_e64 v131, v133, v131, s[38:39]
	ds_bpermute_b32 v133, v167, v134
	s_waitcnt lgkmcnt(0)
	v_add_f32_e32 v131, v131, v133
	v_cndmask_b32_e64 v133, v132, v130, s[38:39]
	v_cndmask_b32_e64 v130, v130, v132, s[38:39]
	ds_bpermute_b32 v132, v167, v133
	s_waitcnt lgkmcnt(0)
	v_add_f32_e32 v130, v130, v132
	v_cndmask_b32_e64 v132, v131, v130, s[40:41]
	v_cndmask_b32_e64 v130, v130, v131, s[40:41]
	ds_bpermute_b32 v131, v168, v132
	s_waitcnt lgkmcnt(0)
	v_add_f32_e32 v130, v130, v131
	ds_bpermute_b32 v131, v169, v130
	s_waitcnt lgkmcnt(0)
	v_add_f32_e32 v130, v130, v131
	ds_bpermute_b32 v131, v170, v130
	s_waitcnt lgkmcnt(0)
	v_add_f32_e32 v130, v130, v131
	ds_bpermute_b32 v131, v171, v130
	s_and_saveexec_b64 s[56:57], s[42:43]
	s_cbranch_execz .LBB0_641
	s_waitcnt lgkmcnt(0)
	v_add_f32_e32 v130, v130, v131
	global_load_dword v131, v[144:145], off
	s_waitcnt vmcnt(0)
	v_add_f32_e32 v130, v130, v131
	v_cmp_ngt_f32_e64 s[46:47], 0, v130
	s_and_saveexec_b64 s[8:9], s[46:47]
	s_xor_b64 s[54:55], exec, s[8:9]
	s_cbranch_execz .LBB0_647
	v_mul_f32_e32 v131, 0xbfb8aa3b, v130
	v_rndne_f32_e32 v132, v131
	s_mov_b32 s8, 0xbfb8aa3b
	v_sub_f32_e32 v133, v131, v132
	v_fma_f32 v131, v130, s8, -v131
	v_fmac_f32_e32 v131, 0xb2a5705f, v130
	v_add_f32_e32 v131, v133, v131
	v_cvt_i32_f32_e32 v132, v132
	v_exp_f32_e32 v131, v131
	s_mov_b32 s8, 0x42ce8ed0
	v_cmp_nlt_f32_e64 s[46:47], s8, v130
	s_mov_b32 s8, 0xc2b17218
	v_ldexp_f32 v131, v131, v132
	v_cndmask_b32_e64 v131, 0, v131, s[46:47]
	v_cmp_ngt_f32_e64 s[46:47], s8, v130
	s_mov_b32 s8, 0x3f2aaaab
	s_nop 0
	v_cndmask_b32_e64 v151, v220, v131, s[46:47]
	v_add_f32_e32 v132, 1.0, v151
	v_add_f32_e32 v130, -1.0, v132
	v_sub_f32_e32 v131, v130, v132
	v_add_f32_e32 v131, 1.0, v131
	v_sub_f32_e32 v130, v151, v130
	v_add_f32_e32 v133, v130, v131
	v_frexp_mant_f32_e32 v134, v132
	v_cvt_f64_f32_e32 v[130:131], v132
	v_frexp_exp_i32_f64_e32 v130, v[130:131]
	v_cmp_gt_f32_e64 s[46:47], s8, v134
	s_mov_b32 s8, 0x3f317218
	s_nop 0
	v_subbrev_co_u32_e64 v138, s[46:47], 0, v130, s[46:47]
	v_sub_u32_e32 v130, 0, v138
	v_ldexp_f32 v131, v132, v130
	v_add_f32_e32 v132, -1.0, v131
	v_add_f32_e32 v134, 1.0, v131
	v_ldexp_f32 v130, v133, v130
	v_add_f32_e32 v133, 1.0, v132
	v_add_f32_e32 v135, -1.0, v134
	v_sub_f32_e32 v133, v131, v133
	v_sub_f32_e32 v131, v131, v135
	v_add_f32_e32 v133, v130, v133
	v_add_f32_e32 v130, v130, v131
	v_add_f32_e32 v139, v134, v130
	v_rcp_f32_e32 v141, v139
	v_sub_f32_e32 v131, v134, v139
	v_add_f32_e32 v140, v130, v131
	v_add_f32_e32 v131, v132, v133
	v_mul_f32_e32 v156, v131, v141
	v_sub_f32_e32 v130, v132, v131
	v_mul_f32_e32 v132, v139, v156
	v_fma_f32 v134, v156, v139, -v132
	v_fmac_f32_e32 v134, v156, v140
	v_add_f32_e32 v153, v133, v130
	v_add_f32_e32 v130, v132, v134
	v_sub_f32_e32 v133, v131, v130
	v_pk_add_f32 v[136:137], v[130:131], v[132:133] neg_lo:[0,1] neg_hi:[0,1]
	v_mov_b32_e32 v135, v130
	v_pk_add_f32 v[130:131], v[136:137], v[134:135] neg_lo:[0,1] neg_hi:[0,1]
	s_nop 0
	v_add_f32_e32 v131, v153, v131
	v_add_f32_e32 v130, v130, v131
	v_add_f32_e32 v131, v133, v130
	v_mul_f32_e32 v153, v141, v131
	v_mul_f32_e32 v132, v139, v153
	v_fma_f32 v134, v153, v139, -v132
	v_fmac_f32_e32 v134, v153, v140
	v_sub_f32_e32 v133, v133, v131
	v_add_f32_e32 v139, v130, v133
	v_add_f32_e32 v130, v132, v134
	v_sub_f32_e32 v133, v131, v130
	v_pk_add_f32 v[136:137], v[130:131], v[132:133] neg_lo:[0,1] neg_hi:[0,1]
	v_mov_b32_e32 v135, v130
	v_pk_add_f32 v[130:131], v[136:137], v[134:135] neg_lo:[0,1] neg_hi:[0,1]
	s_nop 0
	v_add_f32_e32 v131, v139, v131
	v_add_f32_e32 v130, v130, v131
	v_add_f32_e32 v131, v156, v153
	v_add_f32_e32 v130, v133, v130
	v_sub_f32_e32 v132, v131, v156
	v_mul_f32_e32 v130, v141, v130
	v_sub_f32_e32 v132, v153, v132
	v_add_f32_e32 v132, v132, v130
	v_add_f32_e32 v134, v131, v132
	v_mul_f32_e32 v135, v134, v134
	v_fmamk_f32 v130, v135, 0x3e9b6dac, v207
	v_fmaak_f32 v197, v135, v130, 0x3f2aaada
	v_cvt_f32_i32_e32 v130, v138
	v_sub_f32_e32 v131, v134, v131
	v_sub_f32_e32 v131, v132, v131
	v_ldexp_f32 v136, v131, 1
	v_mul_f32_e32 v131, v134, v135
	v_ldexp_f32 v133, v134, 1
	v_pk_mul_f32 v[134:135], v[130:131], v[196:197]
	s_nop 0
	v_fma_f32 v132, v130, s8, -v134
	v_fmac_f32_e32 v132, 0xb102e308, v130
	v_pk_add_f32 v[130:131], v[134:135], v[132:133]
	s_mov_b32 s8, 0x7f800000
	v_sub_f32_e32 v133, v131, v133
	v_sub_f32_e32 v133, v135, v133
	v_add_f32_e32 v137, v136, v133
	v_mov_b32_e32 v136, v134
	v_pk_add_f32 v[134:135], v[130:131], v[134:135] neg_lo:[0,1] neg_hi:[0,1]
	v_pk_add_f32 v[138:139], v[130:131], v[136:137]
	v_mov_b32_e32 v133, v130
	v_mov_b32_e32 v135, v139
	v_pk_add_f32 v[140:141], v[132:133], v[134:135] neg_lo:[0,1] neg_hi:[0,1]
	v_pk_add_f32 v[132:133], v[132:133], v[134:135]
	v_mov_b32_e32 v136, v137
	v_pk_add_f32 v[134:135], v[132:133], v[130:131] op_sel:[1,0] op_sel_hi:[0,1] neg_lo:[0,1] neg_hi:[0,1]
	v_pk_add_f32 v[156:157], v[138:139], v[134:135] op_sel_hi:[1,0] neg_lo:[0,1] neg_hi:[0,1]
	v_mov_b32_e32 v138, v139
	v_mov_b32_e32 v139, v133
	v_pk_mov_b32 v[134:135], v[130:131], v[134:135] op_sel:[1,0]
	v_mov_b32_e32 v137, v130
	v_pk_add_f32 v[134:135], v[138:139], v[134:135] neg_lo:[0,1] neg_hi:[0,1]
	v_mov_b32_e32 v156, v140
	v_pk_add_f32 v[130:131], v[136:137], v[134:135] neg_lo:[0,1] neg_hi:[0,1]
	v_mov_b32_e32 v141, v133
	v_pk_add_f32 v[134:135], v[156:157], v[130:131]
	v_cmp_neq_f32_e64 s[46:47], s8, v151
	v_pk_add_f32 v[136:137], v[134:135], v[134:135] op_sel:[0,1] op_sel_hi:[1,0]
	s_mov_b32 s8, 0x33800000
	v_pk_add_f32 v[132:133], v[132:133], v[136:137] op_sel:[1,0] op_sel_hi:[0,1]
	v_mov_b32_e32 v135, v132
	v_pk_add_f32 v[138:139], v[134:135], v[140:141] neg_lo:[0,1] neg_hi:[0,1]
	v_mov_b32_e32 v131, v136
	v_sub_f32_e32 v133, v134, v138
	v_pk_add_f32 v[130:131], v[130:131], v[138:139] neg_lo:[0,1] neg_hi:[0,1]
	v_sub_f32_e32 v133, v140, v133
	v_add_f32_e32 v130, v130, v133
	v_add_f32_e32 v130, v130, v131
	v_add_f32_e32 v130, v132, v130
	v_cndmask_b32_e64 v130, v220, v130, s[46:47]
	v_cmp_lt_f32_e64 s[46:47], |v151|, s8
	s_nop 1
	v_cndmask_b32_e64 v130, v130, v151, s[46:47]
	v_xor_b32_e32 v131, 0x80000000, v130
